# prep token-mix: log2e scale folded into the per-lane multiplier (two fewer multiplies per token in the special wave)
# speedup vs baseline: 1.0020x; 1.0020x over previous
.LBB0_167:
	s_add_i32 s55, s55, s54
	s_cmpk_lt_i32 s55, 0x400
	s_cselect_b64 s[46:47], -1, 0
	s_cmpk_gt_i32 s55, 0x3ff
	v_mov_b32_e32 v111, v152
	s_cselect_b64 s[42:43], -1, 0
	s_nop 0
	v_cmp_gt_i32_e32 vcc, s57, v111
	v_lshlrev_b32_e32 v54, 1, v111
	s_barrier
	s_and_saveexec_b64 s[44:45], vcc
	s_cbranch_execz .LBB0_301
	s_waitcnt vmcnt(21)
	v_and_b32_e32 v57, 0xffff0000, v1
	v_lshlrev_b32_e32 v56, 16, v1
	v_and_b32_e32 v59, 0xffff0000, v0
	v_lshlrev_b32_e32 v58, 16, v0
	v_pk_add_f32 v[58:59], v[58:59], v[56:57] neg_lo:[0,1] neg_hi:[0,1]
	v_cmp_lt_i32_e64 s[6:7], s58, v111
	v_cmp_lt_u32_e64 s[4:5], s59, v111
	v_cmp_lt_u32_e32 vcc, s60, v111
	s_waitcnt vmcnt(5)
	v_pk_fma_f32 v[58:59], v[50:51], v[58:59], v[56:57]
	s_andn2_b64 s[94:95], s[6:7], s[4:5]
	s_or_b64 s[96:97], s[94:95], vcc
	s_nop 1
	v_cndmask_b32_e64 v236, 1.0, 2.0, s[94:95]
	v_cndmask_b32_e64 v238, 0, -1.0, s[94:95]
	v_mov_b32_e32 v237, 0xbfb8aa3b
	v_mul_f32_e32 v237, v236, v237
	s_cmp_eq_u64 s[6:7], 0
	s_cbranch_scc1 .Lpq0_0
	v_pk_mul_f32 v[234:235], v[58:59], v[236:237] op_sel:[0,1] op_sel_hi:[1,1]
	v_exp_f32_e32 v234, v234
	v_exp_f32_e32 v235, v235
	s_nop 0
	v_pk_add_f32 v[234:235], v[234:235], 1.0 op_sel_hi:[1,0]
	v_rcp_f32_e32 v234, v234
	v_rcp_f32_e32 v235, v235
	s_nop 0
	v_pk_fma_f32 v[234:235], v[234:235], v[236:237], v[238:239] op_sel_hi:[1,0,0]
	v_cndmask_b32_e64 v58, v58, v234, s[96:97]
	v_cndmask_b32_e64 v59, v59, v235, s[96:97]
.Lpq0_0:
	v_lshl_add_u32 v52, v54, 2, 0
	ds_write_b64 v52, v[58:59]
	v_and_b32_e32 v59, 0xffff0000, v2
	v_lshlrev_b32_e32 v58, 16, v2
	v_pk_add_f32 v[56:57], v[56:57], v[58:59] neg_lo:[0,1] neg_hi:[0,1]
	s_nop 0
	v_pk_fma_f32 v[56:57], v[50:51], v[56:57], v[58:59]
	s_cbranch_scc1 .Lpq0_1
	v_pk_mul_f32 v[234:235], v[56:57], v[236:237] op_sel:[0,1] op_sel_hi:[1,1]
	v_exp_f32_e32 v234, v234
	v_exp_f32_e32 v235, v235
	s_nop 0
	v_pk_add_f32 v[234:235], v[234:235], 1.0 op_sel_hi:[1,0]
	v_rcp_f32_e32 v234, v234
	v_rcp_f32_e32 v235, v235
	s_nop 0
	v_pk_fma_f32 v[234:235], v[234:235], v[236:237], v[238:239] op_sel_hi:[1,0,0]
	v_cndmask_b32_e64 v56, v56, v234, s[96:97]
	v_cndmask_b32_e64 v57, v57, v235, s[96:97]
.Lpq0_1:
	ds_write_b64 v52, v[56:57] offset:3600
	v_and_b32_e32 v57, 0xffff0000, v3
	v_lshlrev_b32_e32 v56, 16, v3
	v_pk_add_f32 v[58:59], v[58:59], v[56:57] neg_lo:[0,1] neg_hi:[0,1]
	s_nop 0
	v_pk_fma_f32 v[58:59], v[50:51], v[58:59], v[56:57]
	s_cbranch_scc1 .Lpq0_2
	v_pk_mul_f32 v[234:235], v[58:59], v[236:237] op_sel:[0,1] op_sel_hi:[1,1]
	v_exp_f32_e32 v234, v234
	v_exp_f32_e32 v235, v235
	s_nop 0
	v_pk_add_f32 v[234:235], v[234:235], 1.0 op_sel_hi:[1,0]
	v_rcp_f32_e32 v234, v234
	v_rcp_f32_e32 v235, v235
	s_nop 0
	v_pk_fma_f32 v[234:235], v[234:235], v[236:237], v[238:239] op_sel_hi:[1,0,0]
	v_cndmask_b32_e64 v58, v58, v234, s[96:97]
	v_cndmask_b32_e64 v59, v59, v235, s[96:97]
.Lpq0_2:
	ds_write_b64 v52, v[58:59] offset:7200
	v_and_b32_e32 v59, 0xffff0000, v4
	v_lshlrev_b32_e32 v58, 16, v4
	v_pk_add_f32 v[56:57], v[56:57], v[58:59] neg_lo:[0,1] neg_hi:[0,1]
	s_nop 0
	v_pk_fma_f32 v[56:57], v[50:51], v[56:57], v[58:59]
	s_cbranch_scc1 .Lpq0_3
	v_pk_mul_f32 v[234:235], v[56:57], v[236:237] op_sel:[0,1] op_sel_hi:[1,1]
	v_exp_f32_e32 v234, v234
	v_exp_f32_e32 v235, v235
	s_nop 0
	v_pk_add_f32 v[234:235], v[234:235], 1.0 op_sel_hi:[1,0]
	v_rcp_f32_e32 v234, v234
	v_rcp_f32_e32 v235, v235
	s_nop 0
	v_pk_fma_f32 v[234:235], v[234:235], v[236:237], v[238:239] op_sel_hi:[1,0,0]
	v_cndmask_b32_e64 v56, v56, v234, s[96:97]
	v_cndmask_b32_e64 v57, v57, v235, s[96:97]
.Lpq0_3:
	ds_write_b64 v52, v[56:57] offset:10800
	v_and_b32_e32 v57, 0xffff0000, v5
	v_lshlrev_b32_e32 v56, 16, v5
	v_pk_add_f32 v[58:59], v[58:59], v[56:57] neg_lo:[0,1] neg_hi:[0,1]
	s_nop 0
	v_pk_fma_f32 v[58:59], v[50:51], v[58:59], v[56:57]
	s_cbranch_scc1 .Lpq0_4
	v_pk_mul_f32 v[234:235], v[58:59], v[236:237] op_sel:[0,1] op_sel_hi:[1,1]
	v_exp_f32_e32 v234, v234
	v_exp_f32_e32 v235, v235
	s_nop 0
	v_pk_add_f32 v[234:235], v[234:235], 1.0 op_sel_hi:[1,0]
	v_rcp_f32_e32 v234, v234
	v_rcp_f32_e32 v235, v235
	s_nop 0
	v_pk_fma_f32 v[234:235], v[234:235], v[236:237], v[238:239] op_sel_hi:[1,0,0]
	v_cndmask_b32_e64 v58, v58, v234, s[96:97]
	v_cndmask_b32_e64 v59, v59, v235, s[96:97]
.Lpq0_4:
	ds_write_b64 v52, v[58:59] offset:14400
	v_and_b32_e32 v59, 0xffff0000, v6
	v_lshlrev_b32_e32 v58, 16, v6
	v_pk_add_f32 v[56:57], v[56:57], v[58:59] neg_lo:[0,1] neg_hi:[0,1]
	s_nop 0
	v_pk_fma_f32 v[56:57], v[50:51], v[56:57], v[58:59]
	s_cbranch_scc1 .Lpq0_5
	v_pk_mul_f32 v[234:235], v[56:57], v[236:237] op_sel:[0,1] op_sel_hi:[1,1]
	v_exp_f32_e32 v234, v234
	v_exp_f32_e32 v235, v235
	s_nop 0
	v_pk_add_f32 v[234:235], v[234:235], 1.0 op_sel_hi:[1,0]
	v_rcp_f32_e32 v234, v234
	v_rcp_f32_e32 v235, v235
	s_nop 0
	v_pk_fma_f32 v[234:235], v[234:235], v[236:237], v[238:239] op_sel_hi:[1,0,0]
	v_cndmask_b32_e64 v56, v56, v234, s[96:97]
	v_cndmask_b32_e64 v57, v57, v235, s[96:97]
.Lpq0_5:
	ds_write_b64 v52, v[56:57] offset:18000
	v_and_b32_e32 v57, 0xffff0000, v7
	v_lshlrev_b32_e32 v56, 16, v7
	v_pk_add_f32 v[58:59], v[58:59], v[56:57] neg_lo:[0,1] neg_hi:[0,1]
	s_nop 0
	v_pk_fma_f32 v[58:59], v[50:51], v[58:59], v[56:57]
	s_cbranch_scc1 .Lpq0_6
	v_pk_mul_f32 v[234:235], v[58:59], v[236:237] op_sel:[0,1] op_sel_hi:[1,1]
	v_exp_f32_e32 v234, v234
	v_exp_f32_e32 v235, v235
	s_nop 0
	v_pk_add_f32 v[234:235], v[234:235], 1.0 op_sel_hi:[1,0]
	v_rcp_f32_e32 v234, v234
	v_rcp_f32_e32 v235, v235
	s_nop 0
	v_pk_fma_f32 v[234:235], v[234:235], v[236:237], v[238:239] op_sel_hi:[1,0,0]
	v_cndmask_b32_e64 v58, v58, v234, s[96:97]
	v_cndmask_b32_e64 v59, v59, v235, s[96:97]
.Lpq0_6:
	ds_write_b64 v52, v[58:59] offset:21600
	v_and_b32_e32 v59, 0xffff0000, v8
	v_lshlrev_b32_e32 v58, 16, v8
	v_pk_add_f32 v[56:57], v[56:57], v[58:59] neg_lo:[0,1] neg_hi:[0,1]
	s_nop 0
	v_pk_fma_f32 v[56:57], v[50:51], v[56:57], v[58:59]
	s_cbranch_scc1 .Lpq0_7
	v_pk_mul_f32 v[234:235], v[56:57], v[236:237] op_sel:[0,1] op_sel_hi:[1,1]
	v_exp_f32_e32 v234, v234
	v_exp_f32_e32 v235, v235
	s_nop 0
	v_pk_add_f32 v[234:235], v[234:235], 1.0 op_sel_hi:[1,0]
	v_rcp_f32_e32 v234, v234
	v_rcp_f32_e32 v235, v235
	s_nop 0
	v_pk_fma_f32 v[234:235], v[234:235], v[236:237], v[238:239] op_sel_hi:[1,0,0]
	v_cndmask_b32_e64 v56, v56, v234, s[96:97]
	v_cndmask_b32_e64 v57, v57, v235, s[96:97]
.Lpq0_7:
	ds_write_b64 v52, v[56:57] offset:25200
	v_and_b32_e32 v57, 0xffff0000, v9
	v_lshlrev_b32_e32 v56, 16, v9
	v_pk_add_f32 v[58:59], v[58:59], v[56:57] neg_lo:[0,1] neg_hi:[0,1]
	s_nop 0
	v_pk_fma_f32 v[58:59], v[50:51], v[58:59], v[56:57]
	s_cbranch_scc1 .Lpq0_8
	v_pk_mul_f32 v[234:235], v[58:59], v[236:237] op_sel:[0,1] op_sel_hi:[1,1]
	v_exp_f32_e32 v234, v234
	v_exp_f32_e32 v235, v235
	s_nop 0
	v_pk_add_f32 v[234:235], v[234:235], 1.0 op_sel_hi:[1,0]
	v_rcp_f32_e32 v234, v234
	v_rcp_f32_e32 v235, v235
	s_nop 0
	v_pk_fma_f32 v[234:235], v[234:235], v[236:237], v[238:239] op_sel_hi:[1,0,0]
	v_cndmask_b32_e64 v58, v58, v234, s[96:97]
	v_cndmask_b32_e64 v59, v59, v235, s[96:97]
.Lpq0_8:
	ds_write_b64 v52, v[58:59] offset:28800
	v_and_b32_e32 v59, 0xffff0000, v10
	v_lshlrev_b32_e32 v58, 16, v10
	v_pk_add_f32 v[56:57], v[56:57], v[58:59] neg_lo:[0,1] neg_hi:[0,1]
	s_nop 0
	v_pk_fma_f32 v[56:57], v[50:51], v[56:57], v[58:59]
	s_cbranch_scc1 .Lpq0_9
	v_pk_mul_f32 v[234:235], v[56:57], v[236:237] op_sel:[0,1] op_sel_hi:[1,1]
	v_exp_f32_e32 v234, v234
	v_exp_f32_e32 v235, v235
	s_nop 0
	v_pk_add_f32 v[234:235], v[234:235], 1.0 op_sel_hi:[1,0]
	v_rcp_f32_e32 v234, v234
	v_rcp_f32_e32 v235, v235
	s_nop 0
	v_pk_fma_f32 v[234:235], v[234:235], v[236:237], v[238:239] op_sel_hi:[1,0,0]
	v_cndmask_b32_e64 v56, v56, v234, s[96:97]
	v_cndmask_b32_e64 v57, v57, v235, s[96:97]
.Lpq0_9:
	ds_write_b64 v52, v[56:57] offset:32400
	v_and_b32_e32 v57, 0xffff0000, v11
	v_lshlrev_b32_e32 v56, 16, v11
	v_pk_add_f32 v[58:59], v[58:59], v[56:57] neg_lo:[0,1] neg_hi:[0,1]
	s_nop 0
	v_pk_fma_f32 v[58:59], v[50:51], v[58:59], v[56:57]
	s_cbranch_scc1 .Lpq0_10
	v_pk_mul_f32 v[234:235], v[58:59], v[236:237] op_sel:[0,1] op_sel_hi:[1,1]
	v_exp_f32_e32 v234, v234
	v_exp_f32_e32 v235, v235
	s_nop 0
	v_pk_add_f32 v[234:235], v[234:235], 1.0 op_sel_hi:[1,0]
	v_rcp_f32_e32 v234, v234
	v_rcp_f32_e32 v235, v235
	s_nop 0
	v_pk_fma_f32 v[234:235], v[234:235], v[236:237], v[238:239] op_sel_hi:[1,0,0]
	v_cndmask_b32_e64 v58, v58, v234, s[96:97]
	v_cndmask_b32_e64 v59, v59, v235, s[96:97]
.Lpq0_10:
	ds_write_b64 v52, v[58:59] offset:36000
	v_and_b32_e32 v59, 0xffff0000, v12
	v_lshlrev_b32_e32 v58, 16, v12
	v_pk_add_f32 v[56:57], v[56:57], v[58:59] neg_lo:[0,1] neg_hi:[0,1]
	s_nop 0
	v_pk_fma_f32 v[56:57], v[50:51], v[56:57], v[58:59]
	s_cbranch_scc1 .Lpq0_11
	v_pk_mul_f32 v[234:235], v[56:57], v[236:237] op_sel:[0,1] op_sel_hi:[1,1]
	v_exp_f32_e32 v234, v234
	v_exp_f32_e32 v235, v235
	s_nop 0
	v_pk_add_f32 v[234:235], v[234:235], 1.0 op_sel_hi:[1,0]
	v_rcp_f32_e32 v234, v234
	v_rcp_f32_e32 v235, v235
	s_nop 0
	v_pk_fma_f32 v[234:235], v[234:235], v[236:237], v[238:239] op_sel_hi:[1,0,0]
	v_cndmask_b32_e64 v56, v56, v234, s[96:97]
	v_cndmask_b32_e64 v57, v57, v235, s[96:97]
.Lpq0_11:
	ds_write_b64 v52, v[56:57] offset:39600
	v_and_b32_e32 v57, 0xffff0000, v13
	v_lshlrev_b32_e32 v56, 16, v13
	v_pk_add_f32 v[58:59], v[58:59], v[56:57] neg_lo:[0,1] neg_hi:[0,1]
	s_nop 0
	v_pk_fma_f32 v[58:59], v[50:51], v[58:59], v[56:57]
	s_cbranch_scc1 .Lpq0_12
	v_pk_mul_f32 v[234:235], v[58:59], v[236:237] op_sel:[0,1] op_sel_hi:[1,1]
	v_exp_f32_e32 v234, v234
	v_exp_f32_e32 v235, v235
	s_nop 0
	v_pk_add_f32 v[234:235], v[234:235], 1.0 op_sel_hi:[1,0]
	v_rcp_f32_e32 v234, v234
	v_rcp_f32_e32 v235, v235
	s_nop 0
	v_pk_fma_f32 v[234:235], v[234:235], v[236:237], v[238:239] op_sel_hi:[1,0,0]
	v_cndmask_b32_e64 v58, v58, v234, s[96:97]
	v_cndmask_b32_e64 v59, v59, v235, s[96:97]
.Lpq0_12:
	ds_write_b64 v52, v[58:59] offset:43200
	v_and_b32_e32 v59, 0xffff0000, v14
	v_lshlrev_b32_e32 v58, 16, v14
	v_pk_add_f32 v[56:57], v[56:57], v[58:59] neg_lo:[0,1] neg_hi:[0,1]
	s_nop 0
	v_pk_fma_f32 v[56:57], v[50:51], v[56:57], v[58:59]
	s_cbranch_scc1 .Lpq0_13
	v_pk_mul_f32 v[234:235], v[56:57], v[236:237] op_sel:[0,1] op_sel_hi:[1,1]
	v_exp_f32_e32 v234, v234
	v_exp_f32_e32 v235, v235
	s_nop 0
	v_pk_add_f32 v[234:235], v[234:235], 1.0 op_sel_hi:[1,0]
	v_rcp_f32_e32 v234, v234
	v_rcp_f32_e32 v235, v235
	s_nop 0
	v_pk_fma_f32 v[234:235], v[234:235], v[236:237], v[238:239] op_sel_hi:[1,0,0]
	v_cndmask_b32_e64 v56, v56, v234, s[96:97]
	v_cndmask_b32_e64 v57, v57, v235, s[96:97]
.Lpq0_13:
	ds_write_b64 v52, v[56:57] offset:46800
	v_and_b32_e32 v57, 0xffff0000, v15
	v_lshlrev_b32_e32 v56, 16, v15
	v_pk_add_f32 v[58:59], v[58:59], v[56:57] neg_lo:[0,1] neg_hi:[0,1]
	s_nop 0
	v_pk_fma_f32 v[58:59], v[50:51], v[58:59], v[56:57]
	s_cbranch_scc1 .Lpq0_14
	v_pk_mul_f32 v[234:235], v[58:59], v[236:237] op_sel:[0,1] op_sel_hi:[1,1]
	v_exp_f32_e32 v234, v234
	v_exp_f32_e32 v235, v235
	s_nop 0
	v_pk_add_f32 v[234:235], v[234:235], 1.0 op_sel_hi:[1,0]
	v_rcp_f32_e32 v234, v234
	v_rcp_f32_e32 v235, v235
	s_nop 0
	v_pk_fma_f32 v[234:235], v[234:235], v[236:237], v[238:239] op_sel_hi:[1,0,0]
	v_cndmask_b32_e64 v58, v58, v234, s[96:97]
	v_cndmask_b32_e64 v59, v59, v235, s[96:97]
.Lpq0_14:
	ds_write_b64 v52, v[58:59] offset:50400
	v_and_b32_e32 v59, 0xffff0000, v16
	v_lshlrev_b32_e32 v58, 16, v16
	v_pk_add_f32 v[56:57], v[56:57], v[58:59] neg_lo:[0,1] neg_hi:[0,1]
	s_nop 0
	v_pk_fma_f32 v[56:57], v[50:51], v[56:57], v[58:59]
	s_cbranch_scc1 .Lpq0_15
	v_pk_mul_f32 v[234:235], v[56:57], v[236:237] op_sel:[0,1] op_sel_hi:[1,1]
	v_exp_f32_e32 v234, v234
	v_exp_f32_e32 v235, v235
	s_nop 0
	v_pk_add_f32 v[234:235], v[234:235], 1.0 op_sel_hi:[1,0]
	v_rcp_f32_e32 v234, v234
	v_rcp_f32_e32 v235, v235
	s_nop 0
	v_pk_fma_f32 v[234:235], v[234:235], v[236:237], v[238:239] op_sel_hi:[1,0,0]
	v_cndmask_b32_e64 v56, v56, v234, s[96:97]
	v_cndmask_b32_e64 v57, v57, v235, s[96:97]

.LBB0_1049:
	s_add_i32 s55, s55, s54
	s_cmpk_lt_i32 s55, 0x400
	s_cselect_b64 s[46:47], -1, 0
	s_cmpk_gt_i32 s55, 0x3ff
	v_mov_b32_e32 v139, v152
	s_cselect_b64 s[42:43], -1, 0
	s_nop 0
	v_cmp_gt_i32_e32 vcc, s57, v139
	v_lshlrev_b32_e32 v70, 1, v139
	s_barrier
	s_and_saveexec_b64 s[44:45], vcc
	s_cbranch_execz .LBB0_1183
	s_waitcnt vmcnt(22)
	v_and_b32_e32 v73, 0xffff0000, v1
	v_lshlrev_b32_e32 v72, 16, v1
	v_and_b32_e32 v75, 0xffff0000, v0
	v_lshlrev_b32_e32 v74, 16, v0
	v_pk_add_f32 v[74:75], v[74:75], v[72:73] neg_lo:[0,1] neg_hi:[0,1]
	v_cmp_lt_i32_e64 s[6:7], s58, v139
	v_cmp_lt_u32_e64 s[4:5], s59, v139
	v_cmp_lt_u32_e32 vcc, s60, v139
	s_waitcnt vmcnt(6)
	v_pk_fma_f32 v[74:75], v[66:67], v[74:75], v[72:73]
	s_andn2_b64 s[94:95], s[6:7], s[4:5]
	s_or_b64 s[96:97], s[94:95], vcc
	s_nop 1
	v_cndmask_b32_e64 v236, 1.0, 2.0, s[94:95]
	v_cndmask_b32_e64 v238, 0, -1.0, s[94:95]
	v_mov_b32_e32 v237, 0xbfb8aa3b
	v_mul_f32_e32 v237, v236, v237
	s_cmp_eq_u64 s[6:7], 0
	s_cbranch_scc1 .Lpq1_0
	v_pk_mul_f32 v[234:235], v[74:75], v[236:237] op_sel:[0,1] op_sel_hi:[1,1]
	v_exp_f32_e32 v234, v234
	v_exp_f32_e32 v235, v235
	s_nop 0
	v_pk_add_f32 v[234:235], v[234:235], 1.0 op_sel_hi:[1,0]
	v_rcp_f32_e32 v234, v234
	v_rcp_f32_e32 v235, v235
	s_nop 0
	v_pk_fma_f32 v[234:235], v[234:235], v[236:237], v[238:239] op_sel_hi:[1,0,0]
	v_cndmask_b32_e64 v74, v74, v234, s[96:97]
	v_cndmask_b32_e64 v75, v75, v235, s[96:97]
.Lpq1_0:
	v_lshl_add_u32 v68, v70, 2, 0
	ds_write_b64 v68, v[74:75]
	v_and_b32_e32 v75, 0xffff0000, v2
	v_lshlrev_b32_e32 v74, 16, v2
	v_pk_add_f32 v[72:73], v[72:73], v[74:75] neg_lo:[0,1] neg_hi:[0,1]
	s_nop 0
	v_pk_fma_f32 v[72:73], v[66:67], v[72:73], v[74:75]
	s_cbranch_scc1 .Lpq1_1
	v_pk_mul_f32 v[234:235], v[72:73], v[236:237] op_sel:[0,1] op_sel_hi:[1,1]
	v_exp_f32_e32 v234, v234
	v_exp_f32_e32 v235, v235
	s_nop 0
	v_pk_add_f32 v[234:235], v[234:235], 1.0 op_sel_hi:[1,0]
	v_rcp_f32_e32 v234, v234
	v_rcp_f32_e32 v235, v235
	s_nop 0
	v_pk_fma_f32 v[234:235], v[234:235], v[236:237], v[238:239] op_sel_hi:[1,0,0]
	v_cndmask_b32_e64 v72, v72, v234, s[96:97]
	v_cndmask_b32_e64 v73, v73, v235, s[96:97]
.Lpq1_1:
	ds_write_b64 v68, v[72:73] offset:3600
	v_and_b32_e32 v73, 0xffff0000, v3
	v_lshlrev_b32_e32 v72, 16, v3
	v_pk_add_f32 v[74:75], v[74:75], v[72:73] neg_lo:[0,1] neg_hi:[0,1]
	s_nop 0
	v_pk_fma_f32 v[74:75], v[66:67], v[74:75], v[72:73]
	s_cbranch_scc1 .Lpq1_2
	v_pk_mul_f32 v[234:235], v[74:75], v[236:237] op_sel:[0,1] op_sel_hi:[1,1]
	v_exp_f32_e32 v234, v234
	v_exp_f32_e32 v235, v235
	s_nop 0
	v_pk_add_f32 v[234:235], v[234:235], 1.0 op_sel_hi:[1,0]
	v_rcp_f32_e32 v234, v234
	v_rcp_f32_e32 v235, v235
	s_nop 0
	v_pk_fma_f32 v[234:235], v[234:235], v[236:237], v[238:239] op_sel_hi:[1,0,0]
	v_cndmask_b32_e64 v74, v74, v234, s[96:97]
	v_cndmask_b32_e64 v75, v75, v235, s[96:97]
.Lpq1_2:
	ds_write_b64 v68, v[74:75] offset:7200
	v_and_b32_e32 v75, 0xffff0000, v4
	v_lshlrev_b32_e32 v74, 16, v4
	v_pk_add_f32 v[72:73], v[72:73], v[74:75] neg_lo:[0,1] neg_hi:[0,1]
	s_nop 0
	v_pk_fma_f32 v[72:73], v[66:67], v[72:73], v[74:75]
	s_cbranch_scc1 .Lpq1_3
	v_pk_mul_f32 v[234:235], v[72:73], v[236:237] op_sel:[0,1] op_sel_hi:[1,1]
	v_exp_f32_e32 v234, v234
	v_exp_f32_e32 v235, v235
	s_nop 0
	v_pk_add_f32 v[234:235], v[234:235], 1.0 op_sel_hi:[1,0]
	v_rcp_f32_e32 v234, v234
	v_rcp_f32_e32 v235, v235
	s_nop 0
	v_pk_fma_f32 v[234:235], v[234:235], v[236:237], v[238:239] op_sel_hi:[1,0,0]
	v_cndmask_b32_e64 v72, v72, v234, s[96:97]
	v_cndmask_b32_e64 v73, v73, v235, s[96:97]
.Lpq1_3:
	ds_write_b64 v68, v[72:73] offset:10800
	v_and_b32_e32 v73, 0xffff0000, v5
	v_lshlrev_b32_e32 v72, 16, v5
	v_pk_add_f32 v[74:75], v[74:75], v[72:73] neg_lo:[0,1] neg_hi:[0,1]
	s_nop 0
	v_pk_fma_f32 v[74:75], v[66:67], v[74:75], v[72:73]
	s_cbranch_scc1 .Lpq1_4
	v_pk_mul_f32 v[234:235], v[74:75], v[236:237] op_sel:[0,1] op_sel_hi:[1,1]
	v_exp_f32_e32 v234, v234
	v_exp_f32_e32 v235, v235
	s_nop 0
	v_pk_add_f32 v[234:235], v[234:235], 1.0 op_sel_hi:[1,0]
	v_rcp_f32_e32 v234, v234
	v_rcp_f32_e32 v235, v235
	s_nop 0
	v_pk_fma_f32 v[234:235], v[234:235], v[236:237], v[238:239] op_sel_hi:[1,0,0]
	v_cndmask_b32_e64 v74, v74, v234, s[96:97]
	v_cndmask_b32_e64 v75, v75, v235, s[96:97]
.Lpq1_4:
	ds_write_b64 v68, v[74:75] offset:14400
	v_and_b32_e32 v75, 0xffff0000, v6
	v_lshlrev_b32_e32 v74, 16, v6
	v_pk_add_f32 v[72:73], v[72:73], v[74:75] neg_lo:[0,1] neg_hi:[0,1]
	s_nop 0
	v_pk_fma_f32 v[72:73], v[66:67], v[72:73], v[74:75]
	s_cbranch_scc1 .Lpq1_5
	v_pk_mul_f32 v[234:235], v[72:73], v[236:237] op_sel:[0,1] op_sel_hi:[1,1]
	v_exp_f32_e32 v234, v234
	v_exp_f32_e32 v235, v235
	s_nop 0
	v_pk_add_f32 v[234:235], v[234:235], 1.0 op_sel_hi:[1,0]
	v_rcp_f32_e32 v234, v234
	v_rcp_f32_e32 v235, v235
	s_nop 0
	v_pk_fma_f32 v[234:235], v[234:235], v[236:237], v[238:239] op_sel_hi:[1,0,0]
	v_cndmask_b32_e64 v72, v72, v234, s[96:97]
	v_cndmask_b32_e64 v73, v73, v235, s[96:97]
.Lpq1_5:
	ds_write_b64 v68, v[72:73] offset:18000
	v_and_b32_e32 v73, 0xffff0000, v7
	v_lshlrev_b32_e32 v72, 16, v7
	v_pk_add_f32 v[74:75], v[74:75], v[72:73] neg_lo:[0,1] neg_hi:[0,1]
	s_nop 0
	v_pk_fma_f32 v[74:75], v[66:67], v[74:75], v[72:73]
	s_cbranch_scc1 .Lpq1_6
	v_pk_mul_f32 v[234:235], v[74:75], v[236:237] op_sel:[0,1] op_sel_hi:[1,1]
	v_exp_f32_e32 v234, v234
	v_exp_f32_e32 v235, v235
	s_nop 0
	v_pk_add_f32 v[234:235], v[234:235], 1.0 op_sel_hi:[1,0]
	v_rcp_f32_e32 v234, v234
	v_rcp_f32_e32 v235, v235
	s_nop 0
	v_pk_fma_f32 v[234:235], v[234:235], v[236:237], v[238:239] op_sel_hi:[1,0,0]
	v_cndmask_b32_e64 v74, v74, v234, s[96:97]
	v_cndmask_b32_e64 v75, v75, v235, s[96:97]
.Lpq1_6:
	ds_write_b64 v68, v[74:75] offset:21600
	v_and_b32_e32 v75, 0xffff0000, v8
	v_lshlrev_b32_e32 v74, 16, v8
	v_pk_add_f32 v[72:73], v[72:73], v[74:75] neg_lo:[0,1] neg_hi:[0,1]
	s_nop 0
	v_pk_fma_f32 v[72:73], v[66:67], v[72:73], v[74:75]
	s_cbranch_scc1 .Lpq1_7
	v_pk_mul_f32 v[234:235], v[72:73], v[236:237] op_sel:[0,1] op_sel_hi:[1,1]
	v_exp_f32_e32 v234, v234
	v_exp_f32_e32 v235, v235
	s_nop 0
	v_pk_add_f32 v[234:235], v[234:235], 1.0 op_sel_hi:[1,0]
	v_rcp_f32_e32 v234, v234
	v_rcp_f32_e32 v235, v235
	s_nop 0
	v_pk_fma_f32 v[234:235], v[234:235], v[236:237], v[238:239] op_sel_hi:[1,0,0]
	v_cndmask_b32_e64 v72, v72, v234, s[96:97]
	v_cndmask_b32_e64 v73, v73, v235, s[96:97]
.Lpq1_7:
	ds_write_b64 v68, v[72:73] offset:25200
	v_and_b32_e32 v73, 0xffff0000, v9
	v_lshlrev_b32_e32 v72, 16, v9
	v_pk_add_f32 v[74:75], v[74:75], v[72:73] neg_lo:[0,1] neg_hi:[0,1]
	s_nop 0
	v_pk_fma_f32 v[74:75], v[66:67], v[74:75], v[72:73]
	s_cbranch_scc1 .Lpq1_8
	v_pk_mul_f32 v[234:235], v[74:75], v[236:237] op_sel:[0,1] op_sel_hi:[1,1]
	v_exp_f32_e32 v234, v234
	v_exp_f32_e32 v235, v235
	s_nop 0
	v_pk_add_f32 v[234:235], v[234:235], 1.0 op_sel_hi:[1,0]
	v_rcp_f32_e32 v234, v234
	v_rcp_f32_e32 v235, v235
	s_nop 0
	v_pk_fma_f32 v[234:235], v[234:235], v[236:237], v[238:239] op_sel_hi:[1,0,0]
	v_cndmask_b32_e64 v74, v74, v234, s[96:97]
	v_cndmask_b32_e64 v75, v75, v235, s[96:97]
.Lpq1_8:
	ds_write_b64 v68, v[74:75] offset:28800
	v_and_b32_e32 v75, 0xffff0000, v10
	v_lshlrev_b32_e32 v74, 16, v10
	v_pk_add_f32 v[72:73], v[72:73], v[74:75] neg_lo:[0,1] neg_hi:[0,1]
	s_nop 0
	v_pk_fma_f32 v[72:73], v[66:67], v[72:73], v[74:75]
	s_cbranch_scc1 .Lpq1_9
	v_pk_mul_f32 v[234:235], v[72:73], v[236:237] op_sel:[0,1] op_sel_hi:[1,1]
	v_exp_f32_e32 v234, v234
	v_exp_f32_e32 v235, v235
	s_nop 0
	v_pk_add_f32 v[234:235], v[234:235], 1.0 op_sel_hi:[1,0]
	v_rcp_f32_e32 v234, v234
	v_rcp_f32_e32 v235, v235
	s_nop 0
	v_pk_fma_f32 v[234:235], v[234:235], v[236:237], v[238:239] op_sel_hi:[1,0,0]
	v_cndmask_b32_e64 v72, v72, v234, s[96:97]
	v_cndmask_b32_e64 v73, v73, v235, s[96:97]
.Lpq1_9:
	ds_write_b64 v68, v[72:73] offset:32400
	v_and_b32_e32 v73, 0xffff0000, v11
	v_lshlrev_b32_e32 v72, 16, v11
	v_pk_add_f32 v[74:75], v[74:75], v[72:73] neg_lo:[0,1] neg_hi:[0,1]
	s_nop 0
	v_pk_fma_f32 v[74:75], v[66:67], v[74:75], v[72:73]
	s_cbranch_scc1 .Lpq1_10
	v_pk_mul_f32 v[234:235], v[74:75], v[236:237] op_sel:[0,1] op_sel_hi:[1,1]
	v_exp_f32_e32 v234, v234
	v_exp_f32_e32 v235, v235
	s_nop 0
	v_pk_add_f32 v[234:235], v[234:235], 1.0 op_sel_hi:[1,0]
	v_rcp_f32_e32 v234, v234
	v_rcp_f32_e32 v235, v235
	s_nop 0
	v_pk_fma_f32 v[234:235], v[234:235], v[236:237], v[238:239] op_sel_hi:[1,0,0]
	v_cndmask_b32_e64 v74, v74, v234, s[96:97]
	v_cndmask_b32_e64 v75, v75, v235, s[96:97]
.Lpq1_10:
	ds_write_b64 v68, v[74:75] offset:36000
	v_and_b32_e32 v75, 0xffff0000, v12
	v_lshlrev_b32_e32 v74, 16, v12
	v_pk_add_f32 v[72:73], v[72:73], v[74:75] neg_lo:[0,1] neg_hi:[0,1]
	s_nop 0
	v_pk_fma_f32 v[72:73], v[66:67], v[72:73], v[74:75]
	s_cbranch_scc1 .Lpq1_11
	v_pk_mul_f32 v[234:235], v[72:73], v[236:237] op_sel:[0,1] op_sel_hi:[1,1]
	v_exp_f32_e32 v234, v234
	v_exp_f32_e32 v235, v235
	s_nop 0
	v_pk_add_f32 v[234:235], v[234:235], 1.0 op_sel_hi:[1,0]
	v_rcp_f32_e32 v234, v234
	v_rcp_f32_e32 v235, v235
	s_nop 0
	v_pk_fma_f32 v[234:235], v[234:235], v[236:237], v[238:239] op_sel_hi:[1,0,0]
	v_cndmask_b32_e64 v72, v72, v234, s[96:97]
	v_cndmask_b32_e64 v73, v73, v235, s[96:97]
.Lpq1_11:
	ds_write_b64 v68, v[72:73] offset:39600
	v_and_b32_e32 v73, 0xffff0000, v13
	v_lshlrev_b32_e32 v72, 16, v13
	v_pk_add_f32 v[74:75], v[74:75], v[72:73] neg_lo:[0,1] neg_hi:[0,1]
	s_nop 0
	v_pk_fma_f32 v[74:75], v[66:67], v[74:75], v[72:73]
	s_cbranch_scc1 .Lpq1_12
	v_pk_mul_f32 v[234:235], v[74:75], v[236:237] op_sel:[0,1] op_sel_hi:[1,1]
	v_exp_f32_e32 v234, v234
	v_exp_f32_e32 v235, v235
	s_nop 0
	v_pk_add_f32 v[234:235], v[234:235], 1.0 op_sel_hi:[1,0]
	v_rcp_f32_e32 v234, v234
	v_rcp_f32_e32 v235, v235
	s_nop 0
	v_pk_fma_f32 v[234:235], v[234:235], v[236:237], v[238:239] op_sel_hi:[1,0,0]
	v_cndmask_b32_e64 v74, v74, v234, s[96:97]
	v_cndmask_b32_e64 v75, v75, v235, s[96:97]
.Lpq1_12:
	ds_write_b64 v68, v[74:75] offset:43200
	v_and_b32_e32 v75, 0xffff0000, v14
	v_lshlrev_b32_e32 v74, 16, v14
	v_pk_add_f32 v[72:73], v[72:73], v[74:75] neg_lo:[0,1] neg_hi:[0,1]
	s_nop 0
	v_pk_fma_f32 v[72:73], v[66:67], v[72:73], v[74:75]
	s_cbranch_scc1 .Lpq1_13
	v_pk_mul_f32 v[234:235], v[72:73], v[236:237] op_sel:[0,1] op_sel_hi:[1,1]
	v_exp_f32_e32 v234, v234
	v_exp_f32_e32 v235, v235
	s_nop 0
	v_pk_add_f32 v[234:235], v[234:235], 1.0 op_sel_hi:[1,0]
	v_rcp_f32_e32 v234, v234
	v_rcp_f32_e32 v235, v235
	s_nop 0
	v_pk_fma_f32 v[234:235], v[234:235], v[236:237], v[238:239] op_sel_hi:[1,0,0]
	v_cndmask_b32_e64 v72, v72, v234, s[96:97]
	v_cndmask_b32_e64 v73, v73, v235, s[96:97]
.Lpq1_13:
	ds_write_b64 v68, v[72:73] offset:46800
	v_and_b32_e32 v73, 0xffff0000, v15
	v_lshlrev_b32_e32 v72, 16, v15
	v_pk_add_f32 v[74:75], v[74:75], v[72:73] neg_lo:[0,1] neg_hi:[0,1]
	s_nop 0
	v_pk_fma_f32 v[74:75], v[66:67], v[74:75], v[72:73]
	s_cbranch_scc1 .Lpq1_14
	v_pk_mul_f32 v[234:235], v[74:75], v[236:237] op_sel:[0,1] op_sel_hi:[1,1]
	v_exp_f32_e32 v234, v234
	v_exp_f32_e32 v235, v235
	s_nop 0
	v_pk_add_f32 v[234:235], v[234:235], 1.0 op_sel_hi:[1,0]
	v_rcp_f32_e32 v234, v234
	v_rcp_f32_e32 v235, v235
	s_nop 0
	v_pk_fma_f32 v[234:235], v[234:235], v[236:237], v[238:239] op_sel_hi:[1,0,0]
	v_cndmask_b32_e64 v74, v74, v234, s[96:97]
	v_cndmask_b32_e64 v75, v75, v235, s[96:97]
.Lpq1_14:
	ds_write_b64 v68, v[74:75] offset:50400
	v_and_b32_e32 v75, 0xffff0000, v16
	v_lshlrev_b32_e32 v74, 16, v16
	v_pk_add_f32 v[72:73], v[72:73], v[74:75] neg_lo:[0,1] neg_hi:[0,1]
	s_nop 0
	v_pk_fma_f32 v[72:73], v[66:67], v[72:73], v[74:75]
	s_cbranch_scc1 .Lpq1_15
	v_pk_mul_f32 v[234:235], v[72:73], v[236:237] op_sel:[0,1] op_sel_hi:[1,1]
	v_exp_f32_e32 v234, v234
	v_exp_f32_e32 v235, v235
	s_nop 0
	v_pk_add_f32 v[234:235], v[234:235], 1.0 op_sel_hi:[1,0]
	v_rcp_f32_e32 v234, v234
	v_rcp_f32_e32 v235, v235
	s_nop 0
	v_pk_fma_f32 v[234:235], v[234:235], v[236:237], v[238:239] op_sel_hi:[1,0,0]
	v_cndmask_b32_e64 v72, v72, v234, s[96:97]
	v_cndmask_b32_e64 v73, v73, v235, s[96:97]
